# attention units dealt to the XCD owning their batch: seams 12/14 XCD-local too; seams 2/7/11/15 (only a cross-XCD write-after-read on aliased workspace) keep the rendezvous but skip the L2 write-back
# speedup vs baseline: 1.0347x; 1.0022x over previous
; #define PG8_STAGE(bufoff, gbase, voff) do { _Pragma("unroll") for (int _i = 0; _i < 2; ++_i) \
;         __builtin_amdgcn_global_load_lds((const unsigned*)((const char*)(gbase) + (voff)[_i]), (PG8_LAS unsigned*)(lds + (bufoff) + ldsw + _i * 8192), 16, 0, 0); } while (0)
; template <class Epi, class Sched, bool ALIGN_EPI = false, bool SP2 = false>
; __device__ __forceinline__ void gemm_phase(PG8_LAS unsigned char* lds, const Gemm g, const Sched& S, const Epi& E) {
;     ...
;     for (int i = 0; i < 2; ++i) { int R, C; stage_rc(tid * 16 + i * 8192, R, C); const int Rb = Epi::PERM ? ((R & ~31) + perm32(R & 31)) : R;
;         voffA[i] = (unsigned)(R * K + C) * 2u; voffB[i] = (unsigned)(Rb * K + C) * 2u; }
;     const size_t kstep = (size_t)(BK * 2);
;     const size_t hstep = (size_t)HALF * K * 2;
;     const size_t tstep = 2 * hstep;
;     const unsigned ldsw = (unsigned)wid * 1024u;
;     const int aoff = lds_byte(wr * 64 + fr, fq * 8), boff = lds_byte(wc * 32 + fr, fq * 8);
;     ...
;     Unit cur, nxt; int ui = 0;
;     if (!S.next(0, cur)) return;
;     f32x4 acc[2][2][4][2];
; #pragma unroll
;     for (int a = 0; a < 2; ++a)
; #pragma unroll
;         for (int b = 0; b < 2; ++b)
; #pragma unroll
;             for (int m = 0; m < 4; ++m)
; #pragma unroll
;                 for (int n = 0; n < 2; ++n) acc[a][b][m][n] = (f32x4){0.f, 0.f, 0.f, 0.f};
;     bf16x8 At[4][2], B0[2][2], B1[2][2];
;     const char* cA = (const char*)g.A + (size_t)cur.pm * tstep; const char* cB = (const char*)g.Bt + (size_t)cur.pn * tstep;
;     S.a_ready(cur);
;     if constexpr (SP2) {
;         PG8_STAGE(PG8_SB(0, 0), cB, voffB); PG8_STAGE(PG8_SB(0, 1), cB + hstep, voffB); PG8_STAGE(PG8_SA(0, 0), cA, voffA); PG8_STAGE(PG8_SA(0, 1), cA + hstep, voffA);
.LBB0_196:
	v_lshlrev_b32_e32 v0, 2, v196
	v_and_b32_e32 v0, 28, v0
	v_add_u32_e32 v0, 0x3800, v0
	s_add_u32 s98, s28, 0x180000
	s_addc_u32 s99, s29, 0
	global_load_dword v1, v0, s[98:99] sc1
	s_mov_b32 s100, s22
	s_waitcnt vmcnt(0)
	v_bcnt_u32_b32 v1, v1, 0
	v_cmp_ne_u32_e32 vcc, 1, v1
	s_nop 3
	s_cmp_eq_u64 vcc, 0
	s_cselect_b32 s98, 1, 0
	s_cmpk_eq_u32 s100, 0x100
	s_cselect_b32 s98, s98, 0
	v_writelane_b32 v249, s98, 48
	s_cmp_lt_i32 s30, 2
	s_cselect_b64 s[4:5], -1, 0
	s_add_u32 s36, s28, 0x6800000
	s_addc_u32 s37, s29, 0
	s_add_u32 s40, s28, 0xa800000
	s_addc_u32 s41, s29, 0
	s_and_b64 s[6:7], s[4:5], s[0:1]
	s_andn2_b64 vcc, exec, s[6:7]
	s_cbranch_vccnz .LBB0_231
	s_ashr_i32 s3, s2, 31
	s_cmpk_lt_i32 s2, 0xb00
	s_cbranch_scc0 .Lpro_skip_0
	v_readfirstlane_b32 s5, v197
	s_nop 3
	v_lshrrev_b32_e32 v0, 5, v197
	v_lshrrev_b32_e32 v2, 1, v197
	v_and_b32_e32 v0, 4, v0
	v_bfe_u32 v1, v197, 2, 2
	v_and_b32_e32 v11, 24, v2
	v_or3_b32 v0, v0, v1, v11
	v_lshlrev_b32_e32 v1, 4, v197
	v_add_u32_e32 v8, 0x2000, v1
	v_lshrrev_b32_e32 v2, 7, v8
	s_movk_i32 s0, 0xe0
	v_and_b32_e32 v4, 32, v197
	v_and_or_b32 v3, v2, s0, v0
	v_bitop3_b32 v9, v1, v4, 48 bitop3:0x6c
	v_and_b32_e32 v10, 64, v197
	v_bfe_u32 v12, v197, 2, 4
	s_movk_i32 s0, 0xf0
	v_or_b32_e32 v1, v9, v10
	v_and_or_b32 v2, v2, s0, v12
	v_lshl_or_b32 v130, v2, 11, v1
	v_lshrrev_b32_e32 v2, 3, v197
	s_movk_i32 s0, 0x60
	s_add_u32 s53, s28, 0x800000
	v_and_or_b32 v0, v2, s0, v0
	s_movk_i32 s0, 0x70
	s_addc_u32 s54, s29, 0
	v_lshl_or_b32 v132, v0, 11, v1
	v_and_or_b32 v0, v2, s0, v12
	s_lshr_b32 s0, s3, 29
	s_add_i32 s0, s2, s0
	s_lshr_b32 s8, s5, 6
	s_ashr_i32 s1, s0, 3
	s_and_b32 s0, s0, -8
	s_lshr_b32 s12, s5, 8
	s_lshl_b32 s55, s8, 10
	s_sub_i32 s0, s2, s0
	s_cmp_lt_i32 s0, 0
	s_movk_i32 s56, 0x161
	s_cselect_b32 s4, s56, 0x160
	s_mul_i32 s0, s4, s0
	s_add_i32 s0, s0, s1
	s_mul_hi_i32 s1, s0, 0x2e8ba2e9
	s_lshr_b32 s4, s1, 31
	s_ashr_i32 s1, s1, 5
	s_add_i32 s1, s1, s4
	s_lshl_b32 s9, s1, 3
	s_mulk_i32 s1, 0xb0
	s_sub_i32 s0, s0, s1
	s_sext_i32_i16 s1, s0
	s_bfe_u32 s1, s1, 0x3001c
	s_add_i32 s1, s0, s1
	s_sext_i32_i16 s4, s1
	s_and_b32 s1, s1, 0xfff8
	s_sub_i32 s0, s0, s1
	s_sext_i32_i16 s0, s0
	s_lshr_b32 s4, s4, 3
	s_add_i32 s34, s9, s0
	s_ashr_i32 s35, s34, 31
	s_bfe_i64 s[10:11], s[4:5], 0x100000
	s_lshl_b64 s[0:1], s[34:35], 19
	s_lshl_b64 s[10:11], s[10:11], 19
	s_add_u32 s42, s53, s10
	s_addc_u32 s43, s54, s11
	s_add_i32 s35, s55, 0
	s_add_i32 m0, s35, 0x10000
	v_lshl_or_b32 v128, v3, 11, v1
	global_load_lds_dwordx4 v132, s[42:43]
	s_add_i32 m0, s35, 0x12000
	s_add_u32 s10, s42, 0x40000
	global_load_lds_dwordx4 v128, s[42:43]
	s_addc_u32 s11, s43, 0
	s_add_i32 m0, s35, 0x14000
	v_lshl_or_b32 v134, v0, 11, v1
	global_load_lds_dwordx4 v132, s[10:11]
	s_add_i32 m0, s35, 0x16000
	s_add_u32 s20, s36, s0
	s_addc_u32 s21, s37, s1
	s_add_i32 s57, s35, 0x2000
	global_load_lds_dwordx4 v128, s[10:11]
	s_mov_b32 m0, s35
	s_add_u32 s0, s20, 0x40000
	global_load_lds_dwordx4 v134, s[20:21]
	s_mov_b32 m0, s57
	s_addc_u32 s1, s21, 0
	s_add_i32 s58, s35, 0x4000
	global_load_lds_dwordx4 v130, s[20:21]
	s_mov_b32 m0, s58
	s_add_i32 s59, s35, 0x6000
	global_load_lds_dwordx4 v134, s[0:1]
	s_mov_b32 m0, s59
	v_mov_b32_e32 v133, 0
	global_load_lds_dwordx4 v130, s[0:1]
	s_mov_b32 s98, s12
	s_mov_b32 s99, s4
	s_mov_b32 s100, s8
	v_mov_b32_e32 v240, v10
	v_mov_b32_e32 v241, v11
	v_mov_b32_e32 v242, v12
	v_mov_b32_e32 v243, v8
	v_mov_b32_e32 v244, v9

; __device__ __forceinline__ unsigned xb_ld(unsigned* p)              { return __hip_atomic_load(p, __ATOMIC_RELAXED, __HIP_MEMORY_SCOPE_AGENT); }
; __device__ __forceinline__ unsigned xb_add(unsigned* p, unsigned v) { return __hip_atomic_fetch_add(p, v, __ATOMIC_RELAXED, __HIP_MEMORY_SCOPE_AGENT); }
; #define XB_SPIN(cond, bar) do { unsigned _sp = 0; while (cond) { __builtin_amdgcn_s_sleep(1); \
;     if ((++_sp & 255u) == 0u) { if (xb_ld(&(bar)[XB_TMO])) break; if (_sp > XB_SPIN_CAP) { atomicAdd(&(bar)[XB_TMO], 1u); break; } } } } while (0)
; __device__ __forceinline__ void xcd_barrier(const XcdBarrier& b) {
;     ...
;             __builtin_amdgcn_fence(__ATOMIC_RELEASE, "agent");
;             asm volatile("s_waitcnt vmcnt(0)" ::: "memory");
;             const unsigned og = xb_add(&bar[XB_TOP], 1u);
;             const unsigned tg = og / nx;
;             if (og + 1u == (tg + 1u) * nx) xb_add(&bar[XB_TOPGEN], 1u);
;             else XB_SPIN(xb_ld(&bar[XB_TOPGEN]) == tg, bar);
;             __builtin_amdgcn_fence(__ATOMIC_ACQUIRE, "agent");
;             xb_add(&bar[XB_XGEN(b.x)], 1u);
;             asm volatile("s_waitcnt vmcnt(0)" ::: "memory");
.Lnowb_0:
	s_waitcnt lgkmcnt(0)
	s_waitcnt vmcnt(0)
	v_mbcnt_lo_u32_b32 v1, s8, 0
	v_mbcnt_hi_u32_b32 v1, s9, v1
	v_cmp_eq_u32_e32 vcc, 0, v1
	s_and_saveexec_b64 s[10:11], vcc
	s_cbranch_execz .LBB0_368
	s_bcnt1_i32_b64 s3, s[8:9]
	v_mov_b32_e32 v2, 0x183000
	v_mov_b32_e32 v3, s3
	global_atomic_add v2, v2, v3, s[28:29] offset:1024 sc0

; __device__ __forceinline__ unsigned xb_ld(unsigned* p)              { return __hip_atomic_load(p, __ATOMIC_RELAXED, __HIP_MEMORY_SCOPE_AGENT); }
; __device__ __forceinline__ unsigned xb_add(unsigned* p, unsigned v) { return __hip_atomic_fetch_add(p, v, __ATOMIC_RELAXED, __HIP_MEMORY_SCOPE_AGENT); }
; #define XB_SPIN(cond, bar) do { unsigned _sp = 0; while (cond) { __builtin_amdgcn_s_sleep(1); \
;     if ((++_sp & 255u) == 0u) { if (xb_ld(&(bar)[XB_TMO])) break; if (_sp > XB_SPIN_CAP) { atomicAdd(&(bar)[XB_TMO], 1u); break; } } } } while (0)
; __device__ __forceinline__ void xcd_barrier(const XcdBarrier& b) {
;     ...
;         const unsigned old = xb_add(&bar[XB_XSUB(b.x)], 1u);
;         const unsigned gen = old / nloc;
;         if (old + 1u == (gen + 1u) * nloc) {
;             __builtin_amdgcn_fence(__ATOMIC_RELEASE, "agent");
;             asm volatile("s_waitcnt vmcnt(0)" ::: "memory");
;             const unsigned og = xb_add(&bar[XB_TOP], 1u);
;             const unsigned tg = og / nx;
;             if (og + 1u == (tg + 1u) * nx) xb_add(&bar[XB_TOPGEN], 1u);
;             else XB_SPIN(xb_ld(&bar[XB_TOPGEN]) == tg, bar);
;             __builtin_amdgcn_fence(__ATOMIC_ACQUIRE, "agent");
;             xb_add(&bar[XB_XGEN(b.x)], 1u);
;             asm volatile("s_waitcnt vmcnt(0)" ::: "memory");
.LBB0_1486:
	s_andn2_saveexec_b64 s[6:7], s[6:7]
	s_cbranch_execz .LBB0_1506
	s_mov_b64 s[6:7], exec
	v_readlane_b32 s3, v249, 48
	s_nop 3
	s_cmp_lg_u32 s3, 0
	s_cbranch_scc1 .LBB0_1503
	buffer_wbl2 sc1
	s_waitcnt lgkmcnt(0)
	s_waitcnt vmcnt(0)
	v_mbcnt_lo_u32_b32 v1, s6, 0
	v_mbcnt_hi_u32_b32 v1, s7, v1
	v_cmp_eq_u32_e32 vcc, 0, v1
	s_and_saveexec_b64 s[8:9], vcc
	s_cbranch_execz .LBB0_1489
	s_bcnt1_i32_b64 s3, s[6:7]
	v_mov_b32_e32 v2, 0x183000
	v_mov_b32_e32 v3, s3
	global_atomic_add v2, v2, v3, s[28:29] offset:1024 sc0

; #define LAS __attribute__((address_space(3)))
; __device__ __forceinline__ void attn_unit(LAS unsigned char* lds, const bf16_t* QK, const bf16_t* VTt, const float* KM, bf16_t* OA, int b, int h, int qb, int tid, int lane, int wave) {
;     const int r32 = lane & 31, hf = lane >> 5;
;     const int row0 = b * SEQ + qb * 256 + wave * 32;
;     const char* kg = (const char*)(QK + (size_t)(b * SEQ) * 2048 + 1024 + h * HD);
;     const char* vg = (const char*)(VTt + (size_t)((b * NH + h) * 32) * 8192);
;     unsigned goff[5];
; #pragma unroll
;     for (int j = 0; j < 5; ++j) { int p = wave + 8 * j; p = p > 34 ? 34 : p; const int off = p * 1024 + lane * 16;
;         if (p < 17) { const int r = off / ATT_KROW, cb = off % ATT_KROW; goff[j] = (unsigned)(r * 4096 + (cb < 256 ? cb : 0)); }
;         else { const int o2 = off - ATT_KB, d = o2 / ATT_VROW, cb = o2 % ATT_VROW; goff[j] = (unsigned)(d * 128 + (cb < 128 ? cb : 0)); } }
;     const int ntiles = 4 * (qb + 1);
;     ...
;     ATT_DMA(0, 0); ATT_DMA(1, 1);
;     bf16x8 qf[8];
;     { const bf16_t* qp = QK + (size_t)(row0 + r32) * 2048 + h * HD + hf * 8;
; #pragma unroll
;       for (int ks = 0; ks < 8; ++ks) qf[ks] = *(const bf16x8*)(qp + ks * 16); }
;     unsigned sel = (1u << qb) - 1u;
;     if (qb > 3) {
;         float gate[7];
; #pragma unroll
;         for (int n = 0; n < 7; ++n) { gate[n] = -INFINITY;
;             if (n < qb) { const float* kp = KM + ((size_t)(b * NH + h) * 8 + n) * HD + hf * 8; float s = 0.f;
; #pragma unroll
;                 for (int ks = 0; ks < 8; ++ks) { const f32x4 k0 = *(const f32x4*)(kp + ks * 16), k1 = *(const f32x4*)(kp + ks * 16 + 4); const u32x4 q = __builtin_bit_cast(u32x4, qf[ks]);
;                     s += bf_lo(q.x) * k0.x + bf_hi(q.x) * k0.y + bf_lo(q.y) * k0.z + bf_hi(q.y) * k0.w + bf_lo(q.z) * k1.x + bf_hi(q.z) * k1.y + bf_lo(q.w) * k1.z + bf_hi(q.w) * k1.w; }
;                 gate[n] = s + __shfl_xor(s, 32); } }
; __global__ void __launch_bounds__(NTHREADS, 2) mega_fwd(Args a) {
;     ...
;         for (int pu = vcu; pu < NB * NH * 4; pu += G) { const int bh = pu >> 2, j = pu & 3, b = bh >> 3, h = bh & 7;
;             attn_unit(lds, QK, VT, KM, OA, b, h, 7 - j, tid, lane, wave);
.LBB0_1513:
	s_bfe_u32 s10, s3, 0x30005
	s_lshl_b32 s10, s10, 1
	s_lshr_b32 s0, s3, 8
	s_or_b32 s10, s10, s0
	s_and_b32 s66, s3, 3
	s_lshl_b32 s20, s10, 11
	s_xor_b32 s71, s66, 7
	s_ashr_i32 s21, s20, 31
	s_bfe_u32 s73, s3, 0x30002
	s_lshl_b32 s72, s71, 8
	s_lshl_b64 s[0:1], s[20:21], 12
	s_add_u32 s11, s40, s0
	s_addc_u32 s12, s41, s1
	s_lshl_b32 s0, s10, 3
	s_or_b32 s16, s0, s73
	s_lshl_b32 s0, s16, 5
	s_ashr_i32 s1, s0, 31
	s_lshl_b64 s[0:1], s[0:1], 14
	s_lshl_b32 s44, s73, 8
	s_add_u32 s67, s11, s44
	s_addc_u32 s68, s12, 0
	s_add_u32 s69, s42, s0
	s_addc_u32 s70, s43, s1
	s_lshl_b32 s0, s71, 20
	s_add_u32 s0, s67, s0
	s_addc_u32 s1, s68, 0
	s_add_u32 s12, s0, 0x800
	s_addc_u32 s13, s1, 0
	s_lshl_b32 s0, s71, 16
	s_add_u32 s0, s69, s0
	s_addc_u32 s1, s70, 0
	s_and_b64 s[10:11], s[4:5], exec
	s_cselect_b32 s35, s13, s1
	s_cselect_b32 s34, s12, s0
	s_and_b64 s[10:11], s[6:7], exec
	s_cselect_b32 s47, s13, s1
	s_cselect_b32 s46, s12, s0
	s_and_b64 s[10:11], s[8:9], exec
	s_cselect_b32 s75, s13, s1
	s_cselect_b32 s74, s12, s0
	s_or_b32 s10, s72, 64
	s_lshl_b32 s11, s10, 12
	s_add_u32 s11, s67, s11
	s_addc_u32 s12, s68, 0
	s_add_u32 s17, s11, 0x800
	v_add_u32_e32 v213, s20, v218
	s_addc_u32 s21, s12, 0
	s_lshl_b32 s10, s10, 8
	v_add_u32_e32 v216, s72, v213
	s_add_u32 s10, s69, s10
	v_ashrrev_i32_e32 v217, 31, v216
	s_addc_u32 s11, s70, 0
	v_lshlrev_b64 v[2:3], 12, v[216:217]
	s_and_b64 s[12:13], s[4:5], exec
	v_lshl_add_u64 v[2:3], s[40:41], 0, v[2:3]
	s_cselect_b32 s13, s21, s11
	s_cselect_b32 s12, s17, s10
	s_and_b64 s[14:15], s[6:7], exec
	v_lshl_add_u64 v[2:3], v[2:3], 0, s[44:45]
	s_cselect_b32 s15, s21, s11
	s_cselect_b32 s14, s17, s10
	s_and_b64 s[76:77], s[8:9], exec
	v_lshl_add_u64 v[14:15], v[2:3], 0, v[214:215]
	global_load_dwordx4 v[112:115], v[14:15], off
	global_load_dwordx4 v[116:119], v[14:15], off offset:32
	s_cselect_b32 s21, s21, s11
	s_cselect_b32 s20, s17, s10
	s_ashr_i32 s17, s16, 31
	s_lshl_b64 s[16:17], s[16:17], 12
	v_lshl_add_u64 v[18:19], v[202:203], 0, s[16:17]
	global_load_dwordx4 v[2:5], v[18:19], off
	global_load_dwordx4 v[6:9], v[18:19], off offset:16
	global_load_dwordx4 v[10:13], v[18:19], off offset:64
	global_load_dwordx4 v[36:39], v[18:19], off offset:80
	s_mov_b32 m0, s54
	v_lshl_add_u64 v[16:17], s[34:35], 0, v[204:205]
	global_load_lds_dwordx4 v[16:17], off
	v_lshl_add_u64 v[16:17], s[46:47], 0, v[206:207]
	s_mov_b32 m0, s55
	global_load_dwordx4 v[120:123], v[14:15], off offset:64
	global_load_dwordx4 v[124:127], v[14:15], off offset:96
	s_cmp_lg_u32 s66, 3
	global_load_lds_dwordx4 v[16:17], off
	global_load_dwordx4 v[52:55], v[18:19], off offset:144
	global_load_dwordx4 v[40:43], v[18:19], off offset:128
	v_lshl_add_u64 v[16:17], s[74:75], 0, v[208:209]
	s_mov_b32 m0, s56
	s_waitcnt vmcnt(0)
	v_and_b32_e32 v34, 0xffff0000, v112
	global_load_lds_dwordx4 v[16:17], off
	v_lshl_add_u64 v[16:17], s[0:1], 0, v[198:199]
	s_mov_b32 m0, s57
	v_lshlrev_b32_e32 v20, 16, v112
	global_load_lds_dwordx4 v[16:17], off
	v_lshl_add_u64 v[16:17], s[0:1], 0, v[200:201]
	s_mov_b32 m0, s58
	v_mul_f32_e32 v1, v3, v34
	global_load_lds_dwordx4 v[16:17], off
	v_lshl_add_u64 v[16:17], s[12:13], 0, v[204:205]
	s_mov_b32 m0, s59
	v_fmac_f32_e32 v1, v2, v20
	global_load_lds_dwordx4 v[16:17], off
	v_lshl_add_u64 v[16:17], s[14:15], 0, v[206:207]
	s_mov_b32 m0, s60
	v_lshlrev_b32_e32 v32, 16, v113
	global_load_lds_dwordx4 v[16:17], off
	global_load_dwordx4 v[56:59], v[18:19], off offset:208
	global_load_dwordx4 v[60:63], v[18:19], off offset:192
	v_lshl_add_u64 v[16:17], s[20:21], 0, v[208:209]
	s_mov_b32 m0, s61
	v_fmac_f32_e32 v1, v4, v32
	global_load_lds_dwordx4 v[16:17], off
	v_lshl_add_u64 v[16:17], s[10:11], 0, v[198:199]
	s_mov_b32 m0, s62
	v_and_b32_e32 v30, 0xffff0000, v113
	global_load_lds_dwordx4 v[16:17], off
	v_lshl_add_u64 v[16:17], s[10:11], 0, v[200:201]
	s_mov_b32 m0, s63
	global_load_dwordx4 v[128:131], v[14:15], off offset:128
	global_load_dwordx4 v[132:135], v[14:15], off offset:160
	v_and_b32_e32 v35, 0xffff0000, v116
	global_load_lds_dwordx4 v[16:17], off
	global_load_dwordx4 v[136:139], v[14:15], off offset:192
	global_load_dwordx4 v[140:143], v[14:15], off offset:224
	s_nop 0
	global_load_dwordx4 v[14:17], v[18:19], off offset:272
	global_load_dwordx4 v[64:67], v[18:19], off offset:256
	v_fmac_f32_e32 v1, v5, v30
	v_lshlrev_b32_e32 v28, 16, v114
	v_lshlrev_b32_e32 v21, 16, v116
	v_fmac_f32_e32 v1, v6, v28
	v_mul_f32_e32 v6, v11, v35
	v_lshlrev_b32_e32 v33, 16, v117
	global_load_dwordx4 v[2:5], v[18:19], off offset:336
	global_load_dwordx4 v[68:71], v[18:19], off offset:320
	v_fmac_f32_e32 v6, v10, v21
	v_and_b32_e32 v31, 0xffff0000, v117
	v_fmac_f32_e32 v6, v12, v33
	v_lshlrev_b32_e32 v29, 16, v118
	v_and_b32_e32 v22, 0xffff0000, v114
	v_fmac_f32_e32 v6, v13, v31
	v_and_b32_e32 v23, 0xffff0000, v118
	v_fmac_f32_e32 v1, v7, v22
	v_lshlrev_b32_e32 v26, 16, v115
	v_fmac_f32_e32 v6, v36, v29
	v_lshlrev_b32_e32 v27, 16, v119
	v_fmac_f32_e32 v1, v8, v26
	v_and_b32_e32 v24, 0xffff0000, v115
	v_fmac_f32_e32 v6, v37, v23
	v_and_b32_e32 v25, 0xffff0000, v119
	v_fmac_f32_e32 v1, v9, v24
	v_fmac_f32_e32 v6, v38, v27
	v_and_b32_e32 v38, 0xffff0000, v120
	v_add_f32_e32 v1, 0, v1
	v_fmac_f32_e32 v6, v39, v25
	v_lshlrev_b32_e32 v36, 16, v120
	v_mul_f32_e32 v10, v41, v38
	v_add_f32_e32 v1, v1, v6
	global_load_dwordx4 v[6:9], v[18:19], off offset:400
	global_load_dwordx4 v[72:75], v[18:19], off offset:384
	v_fmac_f32_e32 v10, v40, v36
	v_lshlrev_b32_e32 v50, 16, v121
	v_fmac_f32_e32 v10, v42, v50
	v_and_b32_e32 v48, 0xffff0000, v121
	v_fmac_f32_e32 v10, v43, v48
	v_lshlrev_b32_e32 v46, 16, v122
	v_fmac_f32_e32 v10, v52, v46
	v_and_b32_e32 v40, 0xffff0000, v122
	v_fmac_f32_e32 v10, v53, v40
	v_lshlrev_b32_e32 v44, 16, v123
	v_fmac_f32_e32 v10, v54, v44
	v_and_b32_e32 v42, 0xffff0000, v123
	v_fmac_f32_e32 v10, v55, v42
	v_add_f32_e32 v1, v1, v10
	global_load_dwordx4 v[10:13], v[18:19], off offset:464
	global_load_dwordx4 v[76:79], v[18:19], off offset:448
	global_load_dwordx4 v[80:83], v[18:19], off offset:528
	global_load_dwordx4 v[84:87], v[18:19], off offset:512
	global_load_dwordx4 v[88:91], v[18:19], off offset:592
	global_load_dwordx4 v[92:95], v[18:19], off offset:576
	v_and_b32_e32 v39, 0xffff0000, v124
	v_lshlrev_b32_e32 v37, 16, v124
	v_lshlrev_b32_e32 v51, 16, v125
	v_and_b32_e32 v49, 0xffff0000, v125
	v_lshlrev_b32_e32 v47, 16, v126
	v_and_b32_e32 v41, 0xffff0000, v126
	global_load_dwordx4 v[96:99], v[18:19], off offset:656
	global_load_dwordx4 v[100:103], v[18:19], off offset:640
	v_lshlrev_b32_e32 v45, 16, v127
	v_and_b32_e32 v43, 0xffff0000, v127
	s_cselect_b64 s[20:21], -1, 0
	s_cmp_eq_u32 s66, 3
	s_waitcnt vmcnt(0)
; __device__ __forceinline__ void attn_unit(LAS unsigned char* lds, const bf16_t* QK, const bf16_t* VTt, const float* KM, bf16_t* OA, int b, int h, int qb, int tid, int lane, int wave) {
;     ...
;         for (int n = 0; n < 7; ++n) { gate[n] = -INFINITY;
;             if (n < qb) { const float* kp = KM + ((size_t)(b * NH + h) * 8 + n) * HD + hf * 8; float s = 0.f;
; #pragma unroll
;                 for (int ks = 0; ks < 8; ++ks) { const f32x4 k0 = *(const f32x4*)(kp + ks * 16), k1 = *(const f32x4*)(kp + ks * 16 + 4); const u32x4 q = __builtin_bit_cast(u32x4, qf[ks]);
;                     s += bf_lo(q.x) * k0.x + bf_hi(q.x) * k0.y + bf_lo(q.y) * k0.z + bf_hi(q.y) * k0.w + bf_lo(q.z) * k1.x + bf_hi(q.z) * k1.y + bf_lo(q.w) * k1.z + bf_hi(q.w) * k1.w; }
;                 gate[n] = s + __shfl_xor(s, 32); } }
	v_mul_f32_e32 v52, v61, v39
	v_fmac_f32_e32 v52, v60, v37
	v_fmac_f32_e32 v52, v62, v51
	v_fmac_f32_e32 v52, v63, v49
	v_fmac_f32_e32 v52, v56, v47
	v_fmac_f32_e32 v52, v57, v41
	v_fmac_f32_e32 v52, v58, v45
	v_fmac_f32_e32 v52, v59, v43
	v_add_f32_e32 v1, v1, v52
	v_and_b32_e32 v54, 0xffff0000, v128
	v_lshlrev_b32_e32 v52, 16, v128
	v_lshlrev_b32_e32 v60, 16, v129
	v_and_b32_e32 v58, 0xffff0000, v129
	v_lshlrev_b32_e32 v56, 16, v130
	v_and_b32_e32 v62, 0xffff0000, v130
	v_mul_f32_e32 v104, v65, v54
	v_fmac_f32_e32 v104, v64, v52
	v_fmac_f32_e32 v104, v66, v60
	v_fmac_f32_e32 v104, v67, v58
	v_fmac_f32_e32 v104, v14, v56
	v_fmac_f32_e32 v104, v15, v62
	v_lshlrev_b32_e32 v64, 16, v131
	v_fmac_f32_e32 v104, v16, v64
	v_and_b32_e32 v14, 0xffff0000, v131
	v_fmac_f32_e32 v104, v17, v14
	v_add_f32_e32 v1, v1, v104
	global_load_dwordx4 v[104:107], v[18:19], off offset:720
	global_load_dwordx4 v[108:111], v[18:19], off offset:704
	global_load_dwordx4 v[144:147], v[18:19], off offset:784
	global_load_dwordx4 v[148:151], v[18:19], off offset:768
	global_load_dwordx4 v[152:155], v[18:19], off offset:848
	global_load_dwordx4 v[156:159], v[18:19], off offset:832
	v_and_b32_e32 v55, 0xffff0000, v132
	v_lshlrev_b32_e32 v53, 16, v132
	v_mul_f32_e32 v16, v69, v55
	v_lshlrev_b32_e32 v61, 16, v133
	v_fmac_f32_e32 v16, v68, v53
	v_and_b32_e32 v59, 0xffff0000, v133
	v_fmac_f32_e32 v16, v70, v61
	v_lshlrev_b32_e32 v57, 16, v134
	v_fmac_f32_e32 v16, v71, v59
	v_and_b32_e32 v63, 0xffff0000, v134
	v_fmac_f32_e32 v16, v2, v57
	v_lshlrev_b32_e32 v65, 16, v135
	v_fmac_f32_e32 v16, v3, v63
	v_fmac_f32_e32 v16, v4, v65
	v_and_b32_e32 v4, 0xffff0000, v136
	v_lshlrev_b32_e32 v2, 16, v136
	v_and_b32_e32 v15, 0xffff0000, v135
	v_mul_f32_e32 v168, v73, v4
	v_fmac_f32_e32 v168, v72, v2
	v_lshlrev_b32_e32 v72, 16, v137
	v_fmac_f32_e32 v16, v5, v15
	v_fmac_f32_e32 v168, v74, v72
	v_and_b32_e32 v66, 0xffff0000, v137
	v_add_f32_e32 v1, v1, v16
	v_fmac_f32_e32 v168, v75, v66
	v_lshlrev_b32_e32 v16, 16, v138
	global_load_dwordx4 v[160:163], v[18:19], off offset:912
	global_load_dwordx4 v[164:167], v[18:19], off offset:896
	v_fmac_f32_e32 v168, v6, v16
	v_and_b32_e32 v70, 0xffff0000, v138
	v_fmac_f32_e32 v168, v7, v70
	v_lshlrev_b32_e32 v68, 16, v139
	v_fmac_f32_e32 v168, v8, v68
	v_and_b32_e32 v6, 0xffff0000, v139
	v_and_b32_e32 v5, 0xffff0000, v140
	v_fmac_f32_e32 v168, v9, v6
	v_mul_f32_e32 v9, v85, v34
	v_lshlrev_b32_e32 v3, 16, v140
	v_mul_f32_e32 v8, v77, v5
	v_fmac_f32_e32 v9, v84, v20
	v_lshlrev_b32_e32 v73, 16, v141
	v_fmac_f32_e32 v8, v76, v3
	v_fmac_f32_e32 v9, v86, v32
	v_and_b32_e32 v67, 0xffff0000, v141
	v_fmac_f32_e32 v8, v78, v73
	v_fmac_f32_e32 v9, v87, v30
	v_lshlrev_b32_e32 v17, 16, v142
	v_add_f32_e32 v1, v1, v168
	v_fmac_f32_e32 v8, v79, v67
	global_load_dwordx4 v[74:77], v[18:19], off offset:976
	global_load_dwordx4 v[168:171], v[18:19], off offset:960
	v_fmac_f32_e32 v9, v80, v28
	v_fmac_f32_e32 v8, v10, v17
	v_fmac_f32_e32 v9, v81, v22
	v_mul_f32_e32 v10, v93, v35
	v_fmac_f32_e32 v9, v82, v26
	v_fmac_f32_e32 v10, v92, v21
	v_fmac_f32_e32 v9, v83, v24
	global_load_dwordx4 v[78:81], v[18:19], off offset:1040
	global_load_dwordx4 v[82:85], v[18:19], off offset:1024
	v_fmac_f32_e32 v10, v94, v33
	v_fmac_f32_e32 v10, v95, v31
	v_fmac_f32_e32 v10, v88, v29
	v_fmac_f32_e32 v10, v89, v23
	v_fmac_f32_e32 v10, v90, v27
	v_add_f32_e32 v9, 0, v9
	v_fmac_f32_e32 v10, v91, v25
	global_load_dwordx4 v[86:89], v[18:19], off offset:1104
	global_load_dwordx4 v[90:93], v[18:19], off offset:1088
	v_add_f32_e32 v9, v9, v10
	v_mul_f32_e32 v10, v101, v38
	v_fmac_f32_e32 v10, v100, v36
	v_fmac_f32_e32 v10, v102, v50
	v_fmac_f32_e32 v10, v103, v48
	v_fmac_f32_e32 v10, v96, v46
	v_fmac_f32_e32 v10, v97, v40
	v_fmac_f32_e32 v10, v98, v44
	v_fmac_f32_e32 v10, v99, v42
	global_load_dwordx4 v[94:97], v[18:19], off offset:1168
	global_load_dwordx4 v[98:101], v[18:19], off offset:1152
	v_add_f32_e32 v9, v9, v10
	v_and_b32_e32 v71, 0xffff0000, v142
	s_waitcnt vmcnt(0)
	v_mul_f32_e32 v10, v109, v39
	v_fmac_f32_e32 v10, v108, v37
	v_fmac_f32_e32 v10, v110, v51
	v_fmac_f32_e32 v10, v111, v49
	v_fmac_f32_e32 v10, v104, v47
	v_fmac_f32_e32 v10, v105, v41
	v_fmac_f32_e32 v10, v106, v45
	v_fmac_f32_e32 v10, v107, v43
	global_load_dwordx4 v[102:105], v[18:19], off offset:1232
	global_load_dwordx4 v[106:109], v[18:19], off offset:1216
	v_add_f32_e32 v9, v9, v10
	v_mul_f32_e32 v10, v149, v54
	v_fmac_f32_e32 v10, v148, v52
	v_fmac_f32_e32 v10, v150, v60
	v_fmac_f32_e32 v10, v151, v58
	v_fmac_f32_e32 v10, v144, v56
	v_fmac_f32_e32 v10, v145, v62
	v_fmac_f32_e32 v10, v146, v64
	v_fmac_f32_e32 v10, v147, v14
	global_load_dwordx4 v[144:147], v[18:19], off offset:1296
	global_load_dwordx4 v[148:151], v[18:19], off offset:1280
	v_add_f32_e32 v9, v9, v10
	v_mul_f32_e32 v10, v157, v55
	v_fmac_f32_e32 v10, v156, v53
	v_fmac_f32_e32 v10, v158, v61
	v_fmac_f32_e32 v10, v159, v59
	v_fmac_f32_e32 v10, v152, v57
	v_fmac_f32_e32 v10, v153, v63
	v_fmac_f32_e32 v10, v154, v65
	v_fmac_f32_e32 v10, v155, v15
	global_load_dwordx4 v[152:155], v[18:19], off offset:1360
	global_load_dwordx4 v[156:159], v[18:19], off offset:1344
	v_add_f32_e32 v9, v9, v10
	v_mul_f32_e32 v10, v165, v4
	v_fmac_f32_e32 v10, v164, v2
	v_fmac_f32_e32 v10, v166, v72
	v_fmac_f32_e32 v10, v167, v66
	v_fmac_f32_e32 v10, v160, v16
	v_fmac_f32_e32 v10, v161, v70
	v_fmac_f32_e32 v10, v162, v68
	v_fmac_f32_e32 v10, v163, v6
	global_load_dwordx4 v[160:163], v[18:19], off offset:1424
	global_load_dwordx4 v[164:167], v[18:19], off offset:1408
	v_add_f32_e32 v9, v9, v10
	v_fmac_f32_e32 v8, v11, v71
	v_lshlrev_b32_e32 v69, 16, v143
	v_and_b32_e32 v7, 0xffff0000, v143
; __device__ __forceinline__ void attn_unit(LAS unsigned char* lds, const bf16_t* QK, const bf16_t* VTt, const float* KM, bf16_t* OA, int b, int h, int qb, int tid, int lane, int wave) {
;     ...
;         for (int n = 0; n < 7; ++n) { gate[n] = -INFINITY;
;             if (n < qb) { const float* kp = KM + ((size_t)(b * NH + h) * 8 + n) * HD + hf * 8; float s = 0.f;
; #pragma unroll
;                 for (int ks = 0; ks < 8; ++ks) { const f32x4 k0 = *(const f32x4*)(kp + ks * 16), k1 = *(const f32x4*)(kp + ks * 16 + 4); const u32x4 q = __builtin_bit_cast(u32x4, qf[ks]);
;                     s += bf_lo(q.x) * k0.x + bf_hi(q.x) * k0.y + bf_lo(q.y) * k0.z + bf_hi(q.y) * k0.w + bf_lo(q.z) * k1.x + bf_hi(q.z) * k1.y + bf_lo(q.w) * k1.z + bf_hi(q.w) * k1.w; }
;                 gate[n] = s + __shfl_xor(s, 32); } }
	v_fmac_f32_e32 v8, v12, v69
	v_fmac_f32_e32 v8, v13, v7
	v_add_f32_e32 v1, v1, v8
	ds_bpermute_b32 v8, v219, v1
	v_mul_f32_e32 v10, v169, v5
	v_fmac_f32_e32 v10, v168, v3
	v_fmac_f32_e32 v10, v170, v73
	v_fmac_f32_e32 v10, v171, v67
	v_fmac_f32_e32 v10, v74, v17
	v_fmac_f32_e32 v10, v75, v71
	v_fmac_f32_e32 v10, v76, v69
	v_fmac_f32_e32 v10, v77, v7
	v_mul_f32_e32 v11, v83, v34
	v_fmac_f32_e32 v11, v82, v20
	v_fmac_f32_e32 v11, v84, v32
	v_fmac_f32_e32 v11, v85, v30
	global_load_dwordx4 v[74:77], v[18:19], off offset:1488
	global_load_dwordx4 v[168:171], v[18:19], off offset:1472
	v_fmac_f32_e32 v11, v78, v28
	v_fmac_f32_e32 v11, v79, v22
	v_fmac_f32_e32 v11, v80, v26
	v_mul_f32_e32 v12, v91, v35
	v_fmac_f32_e32 v12, v90, v21
	v_fmac_f32_e32 v11, v81, v24
	global_load_dwordx4 v[78:81], v[18:19], off offset:1552
	global_load_dwordx4 v[82:85], v[18:19], off offset:1536
	v_fmac_f32_e32 v12, v92, v33
	v_fmac_f32_e32 v12, v93, v31
	global_load_dwordx4 v[90:93], v[18:19], off offset:1616
	global_load_dwordx4 v[172:175], v[18:19], off offset:1600
	v_fmac_f32_e32 v12, v86, v29
	v_fmac_f32_e32 v12, v87, v23
	v_fmac_f32_e32 v12, v88, v27
	v_add_f32_e32 v11, 0, v11
	v_fmac_f32_e32 v12, v89, v25
	v_add_f32_e32 v11, v11, v12
	v_mul_f32_e32 v12, v99, v38
	v_fmac_f32_e32 v12, v98, v36
	v_fmac_f32_e32 v12, v100, v50
	v_fmac_f32_e32 v12, v101, v48
	global_load_dwordx4 v[86:89], v[18:19], off offset:1680
	global_load_dwordx4 v[98:101], v[18:19], off offset:1664
	v_fmac_f32_e32 v12, v94, v46
	v_fmac_f32_e32 v12, v95, v40
	v_fmac_f32_e32 v12, v96, v44
	v_fmac_f32_e32 v12, v97, v42
	global_load_dwordx4 v[94:97], v[18:19], off offset:1744
	global_load_dwordx4 v[176:179], v[18:19], off offset:1728
	v_add_f32_e32 v11, v11, v12
	s_waitcnt vmcnt(0)
	v_mul_f32_e32 v12, v107, v39
	v_fmac_f32_e32 v12, v106, v37
	v_fmac_f32_e32 v12, v108, v51
	v_fmac_f32_e32 v12, v109, v49
	v_fmac_f32_e32 v12, v102, v47
	v_fmac_f32_e32 v12, v103, v41
	v_fmac_f32_e32 v12, v104, v45
	v_fmac_f32_e32 v12, v105, v43
	global_load_dwordx4 v[102:105], v[18:19], off offset:1808
	global_load_dwordx4 v[106:109], v[18:19], off offset:1792
	v_add_f32_e32 v11, v11, v12
	v_mul_f32_e32 v12, v149, v54
	v_fmac_f32_e32 v12, v148, v52
	v_fmac_f32_e32 v12, v150, v60
	v_fmac_f32_e32 v12, v151, v58
	global_load_dwordx4 v[148:151], v[18:19], off offset:1872
	global_load_dwordx4 v[180:183], v[18:19], off offset:1856
	v_fmac_f32_e32 v12, v144, v56
	v_fmac_f32_e32 v12, v145, v62
	v_fmac_f32_e32 v12, v146, v64
	v_fmac_f32_e32 v12, v147, v14
	v_add_f32_e32 v11, v11, v12
	v_mul_f32_e32 v12, v157, v55
	v_fmac_f32_e32 v12, v156, v53
	v_fmac_f32_e32 v12, v158, v61
	v_fmac_f32_e32 v12, v159, v59
	global_load_dwordx4 v[144:147], v[18:19], off offset:1936
	global_load_dwordx4 v[156:159], v[18:19], off offset:1920
	v_fmac_f32_e32 v12, v152, v57
	v_fmac_f32_e32 v12, v153, v63
	v_fmac_f32_e32 v12, v154, v65
	v_fmac_f32_e32 v12, v155, v15
	global_load_dwordx4 v[152:155], v[18:19], off offset:2000
	global_load_dwordx4 v[184:187], v[18:19], off offset:1984
	v_add_f32_e32 v11, v11, v12
	v_mul_f32_e32 v12, v165, v4
	v_fmac_f32_e32 v12, v164, v2
	v_fmac_f32_e32 v12, v166, v72
	v_fmac_f32_e32 v12, v167, v66
	v_fmac_f32_e32 v12, v160, v16
	v_fmac_f32_e32 v12, v161, v70
	v_fmac_f32_e32 v12, v162, v68
	v_fmac_f32_e32 v12, v163, v6
	v_add_f32_e32 v11, v11, v12
	v_add_f32_e32 v9, v9, v10
	ds_bpermute_b32 v10, v219, v9
	v_mul_f32_e32 v12, v169, v5
	v_fmac_f32_e32 v12, v168, v3
	v_fmac_f32_e32 v12, v170, v73
	v_fmac_f32_e32 v12, v171, v67
	v_fmac_f32_e32 v12, v74, v17
	v_fmac_f32_e32 v12, v75, v71
	v_fmac_f32_e32 v12, v76, v69
	v_mul_f32_e32 v13, v83, v34
	v_fmac_f32_e32 v13, v82, v20
	v_fmac_f32_e32 v13, v84, v32
	v_mul_f32_e32 v74, v173, v35
	v_fmac_f32_e32 v74, v172, v21
	v_fmac_f32_e32 v13, v85, v30
	v_fmac_f32_e32 v74, v174, v33
	v_fmac_f32_e32 v13, v78, v28
	v_fmac_f32_e32 v74, v175, v31
	v_fmac_f32_e32 v13, v79, v22
	v_fmac_f32_e32 v74, v90, v29
	v_fmac_f32_e32 v13, v80, v26
	v_fmac_f32_e32 v74, v91, v23
	v_fmac_f32_e32 v13, v81, v24
	v_fmac_f32_e32 v74, v92, v27
	v_add_f32_e32 v13, 0, v13
	v_fmac_f32_e32 v74, v93, v25
	v_add_f32_e32 v13, v13, v74
	v_mul_f32_e32 v74, v99, v38
	v_fmac_f32_e32 v74, v98, v36
	v_fmac_f32_e32 v74, v100, v50
	v_fmac_f32_e32 v74, v101, v48
	v_fmac_f32_e32 v74, v86, v46
	v_fmac_f32_e32 v74, v87, v40
	v_fmac_f32_e32 v74, v88, v44
	v_fmac_f32_e32 v74, v89, v42
	v_add_f32_e32 v13, v13, v74
	v_mul_f32_e32 v74, v177, v39
	v_fmac_f32_e32 v74, v176, v37
	v_fmac_f32_e32 v74, v178, v51
	v_fmac_f32_e32 v74, v179, v49
	v_fmac_f32_e32 v74, v94, v47
	v_fmac_f32_e32 v74, v95, v41
	v_fmac_f32_e32 v74, v96, v45
	v_fmac_f32_e32 v74, v97, v43
	v_add_f32_e32 v13, v13, v74
	s_waitcnt vmcnt(0)
	v_mul_f32_e32 v74, v107, v54
	v_fmac_f32_e32 v74, v106, v52
	v_fmac_f32_e32 v74, v108, v60
	v_fmac_f32_e32 v74, v109, v58
	v_fmac_f32_e32 v74, v102, v56
	v_fmac_f32_e32 v74, v103, v62
	v_fmac_f32_e32 v74, v104, v64
	v_fmac_f32_e32 v74, v105, v14
	v_add_f32_e32 v13, v13, v74
	v_mul_f32_e32 v74, v181, v55
	v_fmac_f32_e32 v74, v180, v53
	v_fmac_f32_e32 v74, v182, v61
	v_fmac_f32_e32 v74, v183, v59
	v_fmac_f32_e32 v74, v148, v57
	v_fmac_f32_e32 v74, v149, v63
	v_fmac_f32_e32 v74, v150, v65
	v_fmac_f32_e32 v74, v151, v15
	v_add_f32_e32 v13, v13, v74
	v_mul_f32_e32 v74, v157, v4
	v_fmac_f32_e32 v74, v156, v2
	v_fmac_f32_e32 v74, v158, v72
	v_fmac_f32_e32 v74, v159, v66
	v_fmac_f32_e32 v74, v144, v16
	v_fmac_f32_e32 v74, v145, v70
	v_fmac_f32_e32 v74, v146, v68
	v_fmac_f32_e32 v74, v147, v6
	v_add_f32_e32 v13, v13, v74
	v_mul_f32_e32 v74, v185, v5
	v_fmac_f32_e32 v74, v184, v3
	v_fmac_f32_e32 v74, v186, v73
	v_fmac_f32_e32 v74, v187, v67
	v_fmac_f32_e32 v74, v152, v17
	v_fmac_f32_e32 v74, v153, v71
	v_fmac_f32_e32 v74, v154, v69
	v_fmac_f32_e32 v12, v77, v7
	v_fmac_f32_e32 v74, v155, v7
	v_add_f32_e32 v11, v11, v12
	v_add_f32_e32 v13, v13, v74
	ds_bpermute_b32 v12, v219, v11
	ds_bpermute_b32 v74, v219, v13
	v_mov_b32_e32 v75, 0xff800000
	s_cbranch_scc1 .LBB0_1515
; __device__ __forceinline__ void attn_unit(LAS unsigned char* lds, const bf16_t* QK, const bf16_t* VTt, const float* KM, bf16_t* OA, int b, int h, int qb, int tid, int lane, int wave) {
;     ...
;         for (int n = 0; n < 7; ++n) { gate[n] = -INFINITY;
;             if (n < qb) { const float* kp = KM + ((size_t)(b * NH + h) * 8 + n) * HD + hf * 8; float s = 0.f;
; #pragma unroll
;                 for (int ks = 0; ks < 8; ++ks) { const f32x4 k0 = *(const f32x4*)(kp + ks * 16), k1 = *(const f32x4*)(kp + ks * 16 + 4); const u32x4 q = __builtin_bit_cast(u32x4, qf[ks]);
;                     s += bf_lo(q.x) * k0.x + bf_hi(q.x) * k0.y + bf_lo(q.y) * k0.z + bf_hi(q.y) * k0.w + bf_lo(q.z) * k1.x + bf_hi(q.z) * k1.y + bf_lo(q.w) * k1.z + bf_hi(q.w) * k1.w; }
;                 gate[n] = s + __shfl_xor(s, 32); } }
	global_load_dwordx4 v[76:79], v[18:19], off offset:2048
	global_load_dwordx4 v[80:83], v[18:19], off offset:2112
	global_load_dwordx4 v[84:87], v[18:19], off offset:2064
	global_load_dwordx4 v[88:91], v[18:19], off offset:2128
	global_load_dwordx4 v[92:95], v[18:19], off offset:2176
	global_load_dwordx4 v[96:99], v[18:19], off offset:2240
	global_load_dwordx4 v[100:103], v[18:19], off offset:2192
	global_load_dwordx4 v[104:107], v[18:19], off offset:2256
	global_load_dwordx4 v[108:111], v[18:19], off offset:2304
	global_load_dwordx4 v[144:147], v[18:19], off offset:2368
	global_load_dwordx4 v[148:151], v[18:19], off offset:2320
	global_load_dwordx4 v[152:155], v[18:19], off offset:2384
	global_load_dwordx4 v[156:159], v[18:19], off offset:2432
	global_load_dwordx4 v[160:163], v[18:19], off offset:2496
	global_load_dwordx4 v[164:167], v[18:19], off offset:2448
	global_load_dwordx4 v[168:171], v[18:19], off offset:2512
	s_waitcnt vmcnt(0)
	v_mov_b32_e32 v172, v76
	v_mov_b32_e32 v173, v80
	v_mov_b32_e32 v80, v77
	v_pk_mul_f32 v[80:81], v[80:81], v[34:35]
	v_mov_b32_e32 v76, v78
	v_mov_b32_e32 v77, v82
	v_mov_b32_e32 v82, v79
	v_mov_b32_e32 v79, v88
	v_mov_b32_e32 v88, v85
	v_mov_b32_e32 v85, v90
	v_mov_b32_e32 v90, v87
	v_mov_b32_e32 v87, v96
	v_mov_b32_e32 v96, v93
	v_pk_fma_f32 v[80:81], v[172:173], v[20:21], v[80:81]
	v_mov_b32_e32 v78, v84
	v_mov_b32_e32 v84, v86
	v_mov_b32_e32 v86, v92
	v_pk_mul_f32 v[96:97], v[96:97], v[38:39]
	v_pk_fma_f32 v[76:77], v[76:77], v[32:33], v[80:81]
	v_mov_b32_e32 v92, v94
	v_mov_b32_e32 v93, v98
	v_mov_b32_e32 v98, v95
	v_mov_b32_e32 v95, v104
	v_mov_b32_e32 v104, v101
	v_mov_b32_e32 v101, v106
	v_mov_b32_e32 v106, v103
	v_mov_b32_e32 v103, v144
	v_mov_b32_e32 v144, v109
	v_pk_fma_f32 v[86:87], v[86:87], v[36:37], v[96:97]
	v_pk_fma_f32 v[76:77], v[82:83], v[30:31], v[76:77]
	v_mov_b32_e32 v94, v100
	v_mov_b32_e32 v100, v102
	v_mov_b32_e32 v102, v108
	v_pk_mul_f32 v[144:145], v[144:145], v[54:55]
	v_pk_fma_f32 v[80:81], v[92:93], v[50:51], v[86:87]
	v_pk_fma_f32 v[76:77], v[78:79], v[28:29], v[76:77]
	v_mov_b32_e32 v108, v110
	v_mov_b32_e32 v109, v146
	v_mov_b32_e32 v146, v111
	v_mov_b32_e32 v111, v152
	v_mov_b32_e32 v152, v149
	v_mov_b32_e32 v149, v154
	v_mov_b32_e32 v154, v151
	v_mov_b32_e32 v151, v160
	v_mov_b32_e32 v160, v157
	v_pk_fma_f32 v[96:97], v[102:103], v[52:53], v[144:145]
	v_pk_fma_f32 v[80:81], v[98:99], v[48:49], v[80:81]
	v_pk_fma_f32 v[76:77], v[88:89], v[22:23], v[76:77]
	v_mov_b32_e32 v110, v148
	v_mov_b32_e32 v148, v150
	v_mov_b32_e32 v150, v156
	v_pk_mul_f32 v[160:161], v[160:161], v[4:5]
	v_pk_fma_f32 v[86:87], v[108:109], v[60:61], v[96:97]
	v_pk_fma_f32 v[78:79], v[94:95], v[46:47], v[80:81]
	v_pk_fma_f32 v[76:77], v[84:85], v[26:27], v[76:77]
	v_mov_b32_e32 v156, v158
	v_mov_b32_e32 v157, v162
	v_pk_fma_f32 v[102:103], v[150:151], v[2:3], v[160:161]
	v_pk_fma_f32 v[82:83], v[146:147], v[58:59], v[86:87]
	v_pk_fma_f32 v[78:79], v[104:105], v[40:41], v[78:79]
	v_pk_fma_f32 v[76:77], v[90:91], v[24:25], v[76:77]
	v_mov_b32_e32 v162, v159
	v_pk_fma_f32 v[92:93], v[156:157], v[72:73], v[102:103]
	v_pk_fma_f32 v[80:81], v[110:111], v[56:57], v[82:83]
	v_pk_fma_f32 v[78:79], v[100:101], v[44:45], v[78:79]
	v_add_f32_e32 v75, 0, v76
	v_mov_b32_e32 v158, v164
	v_mov_b32_e32 v159, v168
	v_pk_fma_f32 v[86:87], v[162:163], v[66:67], v[92:93]
	v_pk_fma_f32 v[80:81], v[152:153], v[62:63], v[80:81]
	v_pk_fma_f32 v[78:79], v[106:107], v[42:43], v[78:79]
	v_add_f32_e32 v75, v75, v77
	v_pk_fma_f32 v[82:83], v[158:159], v[16:17], v[86:87]
	v_pk_fma_f32 v[80:81], v[148:149], v[64:65], v[80:81]
	v_add_f32_e32 v75, v75, v78
	v_mov_b32_e32 v168, v165
	v_pk_fma_f32 v[80:81], v[154:155], v[14:15], v[80:81]
	v_add_f32_e32 v75, v75, v79
	v_pk_fma_f32 v[76:77], v[168:169], v[70:71], v[82:83]
	v_mov_b32_e32 v78, v166
	v_mov_b32_e32 v79, v170
	v_add_f32_e32 v75, v75, v80
	v_pk_fma_f32 v[76:77], v[78:79], v[68:69], v[76:77]
	v_mov_b32_e32 v170, v167
	v_add_f32_e32 v75, v75, v81
	v_pk_fma_f32 v[76:77], v[170:171], v[6:7], v[76:77]
	s_nop 0
	v_add_f32_e32 v75, v75, v76
	v_add_f32_e32 v75, v75, v77
	ds_bpermute_b32 v76, v219, v75
	s_waitcnt lgkmcnt(0)
	v_add_f32_e32 v75, v75, v76
